# LDS-DMA lane offsets: second 8 KB slab derived from the first (row+64, same column) instead of recomputed, dead VALU cone removed (152 instrs, 9 prologue sites); on top of v46
# baseline (speedup 1.0000x reference)
; #define WAIT_V8(n) asm volatile("s_waitcnt vmcnt(" #n ")" ::: "memory")
; #define BAR8 __builtin_amdgcn_s_barrier()
;     ...
;   const int brow = m0, bcol = n0;
;   const int wid = t >> 6, lane = t & 63, wr = wid >> 2, wc = wid & 3, fr = lane & 15, fq = lane >> 4;
;   f32x4 acc[2][2][4][2];
;   {
;     float zinit = 0.f;
;     asm volatile("" : "+v"(zinit));
; #pragma unroll
;     for (int a = 0; a < 2; ++a)
; #pragma unroll
;       for (int b = 0; b < 2; ++b)
; #pragma unroll
;         for (int m = 0; m < 4; ++m)
; #pragma unroll
;           for (int n = 0; n < 2; ++n)
; #pragma unroll
;             for (int j = 0; j < 4; ++j) acc[a][b][m][n][j] = zinit;
;   }
;   bf16x8 At[4][2], B0[2][2], B1[2][2];
;   const int nt = K / 64;
;   if (!pre) {
;     STAGE8(SB8(0, 0), Bt, K, bcol, 0); STAGE8(SA8(0, 0), A, lda, brow, 0);
;     STAGE8(SB8(0, 1), Bt, K, bcol + 128, 0); STAGE8(SA8(0, 1), A, lda, brow + 128, 0);
;   }
;   if (wr == 1) BAR8;
;   WAIT_V8(4); BAR8;
;   STAGE8(SB8(1, 0), Bt, K, bcol, 1); STAGE8(SA8(1, 0), A, lda, brow, 1); STAGE8(SB8(1, 1), Bt, K, bcol + 128, 1);
.LBB0_188:
	s_and_b32 s0, s25, 63
	s_lshl_b32 s30, s0, 19
	s_and_b32 s0, s24, 0xffffff00
	s_ashr_i32 s1, s0, 31
	s_lshl_b64 s[56:57], s[0:1], 11
	s_mov_b32 s0, 25
	s_ashr_i32 s1, s0, 31
	s_and_b32 s20, s33, 63
	s_lshl_b64 s[0:1], s[0:1], 3
	s_add_u32 s0, s70, s0
	s_addc_u32 s1, s71, s1
	v_readlane_b32 s0, v255, 60
	v_readlane_b32 s1, v255, 61
	s_nop 4
	v_readlane_b32 s12, v254, 35
	s_mov_b32 s31, s12
	v_readlane_b32 s13, v254, 36
	v_readlane_b32 s14, v254, 37
	s_waitcnt lgkmcnt(0)
	s_add_u32 s54, s0, 0xf640000
	s_mov_b32 s0, 25
	s_addc_u32 s55, s1, 0
	s_ashr_i32 s1, s0, 31
	s_lshl_b64 s[0:1], s[0:1], 3
	s_add_u32 s0, s70, s0
	s_addc_u32 s1, s71, s1
	v_readlane_b32 s0, v255, 60
	v_readlane_b32 s1, v255, 61
	s_nop 4
	v_readlane_b32 s15, v254, 38
	s_waitcnt lgkmcnt(0)
	s_add_u32 s50, s0, 0x2000000
	s_addc_u32 s51, s1, 0
	s_lshl_b32 s0, s33, 2
	s_lshl_b32 s36, s20, 8
	s_and_b32 s52, s0, 0xffffff00
	s_andn2_b64 vcc, exec, s[40:41]
	s_mov_b64 s[0:1], -1
	s_cbranch_vccnz .LBB0_238
	s_mov_b32 s0, 4
	s_ashr_i32 s1, s0, 31
	s_lshl_b64 s[0:1], s[0:1], 3
	s_add_u32 s0, s70, s0
	s_addc_u32 s1, s71, s1
	s_mov_b32 s2, 5
	s_load_dwordx2 s[0:1], s[0:1], 0x0
	s_ashr_i32 s3, s2, 31
	s_lshl_b64 s[2:3], s[2:3], 3
	s_add_u32 s2, s70, s2
	s_addc_u32 s3, s71, s3
	s_mov_b32 s4, 25
	s_load_dwordx2 s[2:3], s[2:3], 0x0
	s_ashr_i32 s5, s4, 31
	s_lshl_b64 s[4:5], s[4:5], 3
	s_add_u32 s4, s70, s4
	s_addc_u32 s5, s71, s5
	v_mov_b32_e32 v3, v224
	v_readlane_b32 s12, v255, 60
	v_readlane_b32 s13, v255, 61
	s_nop 4
	s_ashr_i32 s53, s52, 31
	v_bfe_i32 v1, v3, 27, 1
	s_waitcnt vmcnt(10)
	v_lshlrev_b32_e32 v150, 4, v3
	s_nop 0
	v_readfirstlane_b32 s100, v150
	v_lshrrev_b32_e32 v1, 22, v1
	v_add_u32_e32 v1, v150, v1
	v_and_b32_e32 v1, 0xfffffc00, v1
	v_ashrrev_i32_e32 v0, 31, v3
	v_sub_u32_e32 v1, v150, v1
	v_lshrrev_b32_e32 v0, 26, v0
	v_lshrrev_b32_e32 v5, 4, v1
	v_add_u32_e32 v0, v3, v0
	v_bitop3_b32 v5, v5, v1, 32 bitop3:0x6c
	v_ashrrev_i32_e32 v1, 31, v1
	v_ashrrev_i32_e32 v0, 6, v0
	v_lshrrev_b32_e32 v1, 26, v1
	v_lshlrev_b32_e32 v6, 3, v0
	v_add_u32_e32 v1, v5, v1
	v_and_b32_e32 v6, -16, v6
	v_ashrrev_i32_e32 v1, 6, v1
	v_add_u32_e32 v6, v1, v6
	v_mul_i32_i24_e32 v1, 64, v1
	v_lshlrev_b32_e32 v0, 5, v0
	v_sub_u32_e32 v1, v5, v1
	v_mov_b32_e32 v14, 1
	s_waitcnt vmcnt(9)
	s_lshl_b64 s[4:5], s[52:53], 11
	v_readlane_b32 s21, v254, 44
	v_and_b32_e32 v0, 32, v0
	v_ashrrev_i16_sdwa v1, v14, sext(v1) dst_sel:DWORD dst_unused:UNUSED_PAD src0_sel:DWORD src1_sel:BYTE_0
	s_add_u32 s4, s21, s4
	v_readlane_b32 s27, v254, 45
	v_add_u32_sdwa v0, v0, sext(v1) dst_sel:DWORD dst_unused:UNUSED_PAD src0_sel:DWORD src1_sel:WORD_0
	v_ashrrev_i32_e32 v7, 31, v6
	s_addc_u32 s5, s27, s5
	v_lshlrev_b64 v[132:133], 11, v[6:7]
	v_ashrrev_i32_e32 v1, 31, v0
	v_lshl_add_u64 v[8:9], s[4:5], 0, v[132:133]
	v_lshlrev_b64 v[6:7], 1, v[0:1]
	v_lshl_add_u64 v[10:11], v[8:9], 0, v[6:7]
	v_lshrrev_b32_e32 v134, 1, v6
	v_add_u32_e32 v136, 0x20000, v132
	v_mov_b32_e32 v137, v133
	s_waitcnt vmcnt(8)
	s_or_b32 m0, s100, 0x10000
	v_lshl_add_u64 v[12:13], s[4:5], 0, v[136:137]
	global_load_lds_dwordx4 v[10:11], off
	s_or_b32 m0, s100, 0x12000
	s_lshl_b32 s4, s20, 19
	v_mov_b32_e32 v135, v7
	s_waitcnt lgkmcnt(0)
	s_add_u32 s4, s12, s4
	v_mov_b64_e32 v[8:9], v[6:7]
	s_addc_u32 s5, s13, 0
	v_lshl_add_u64 v[12:13], v[12:13], 0, v[8:9]
	v_lshl_add_u64 v[14:15], s[4:5], 0, v[132:133]
	s_or_b32 s58, s52, 0x80
	global_load_lds_dwordx4 v[12:13], off
	v_lshl_add_u64 v[14:15], v[14:15], 0, v[6:7]
	s_mov_b32 m0, s100
	s_ashr_i32 s59, s58, 31
	global_load_lds_dwordx4 v[14:15], off
	s_or_b32 m0, s100, 0x2000
	s_lshl_b64 s[14:15], s[58:59], 11
	s_add_u32 s14, s21, s14
	v_lshl_add_u64 v[16:17], s[4:5], 0, v[136:137]
	s_addc_u32 s15, s27, s15
	v_lshl_add_u64 v[16:17], v[16:17], 0, v[8:9]
	v_lshl_add_u64 v[18:19], s[14:15], 0, v[132:133]
	global_load_lds_dwordx4 v[16:17], off
	v_lshl_add_u64 v[18:19], v[18:19], 0, v[6:7]
	s_or_b32 m0, s100, 0x14000
	v_lshl_add_u64 v[20:21], s[14:15], 0, v[136:137]
	global_load_lds_dwordx4 v[18:19], off
	s_or_b32 m0, s100, 0x16000
	s_add_u32 s14, s4, 0x40000
	s_addc_u32 s15, s5, 0
	v_lshl_add_u64 v[20:21], v[20:21], 0, v[8:9]
	v_lshl_add_u64 v[22:23], s[14:15], 0, v[132:133]
	global_load_lds_dwordx4 v[20:21], off
	v_lshl_add_u64 v[22:23], v[22:23], 0, v[6:7]
	s_or_b32 m0, s100, 0x4000
	global_load_lds_dwordx4 v[22:23], off
	v_lshl_add_u64 v[22:23], s[14:15], 0, v[136:137]
	v_lshl_add_u64 v[22:23], v[22:23], 0, v[8:9]
	s_or_b32 m0, s100, 0x6000
	v_ashrrev_i32_e32 v5, 8, v3
	global_load_lds_dwordx4 v[22:23], off
	v_cmp_eq_u32_e32 vcc, 1, v5
	s_and_saveexec_b64 s[14:15], vcc
	s_cbranch_execz .LBB0_191
	s_barrier

; #define WAIT_V8(n) asm volatile("s_waitcnt vmcnt(" #n ")" ::: "memory")
; #define BAR8 __builtin_amdgcn_s_barrier()
;     ...
;   const int brow = m0, bcol = n0;
;   const int wid = t >> 6, lane = t & 63, wr = wid >> 2, wc = wid & 3, fr = lane & 15, fq = lane >> 4;
;   f32x4 acc[2][2][4][2];
;   {
;     float zinit = 0.f;
;     asm volatile("" : "+v"(zinit));
; #pragma unroll
;     for (int a = 0; a < 2; ++a)
; #pragma unroll
;       for (int b = 0; b < 2; ++b)
; #pragma unroll
;         for (int m = 0; m < 4; ++m)
; #pragma unroll
;           for (int n = 0; n < 2; ++n)
; #pragma unroll
;             for (int j = 0; j < 4; ++j) acc[a][b][m][n][j] = zinit;
;   }
;   bf16x8 At[4][2], B0[2][2], B1[2][2];
;   const int nt = K / 64;
;   if (!pre) {
;     STAGE8(SB8(0, 0), Bt, K, bcol, 0); STAGE8(SA8(0, 0), A, lda, brow, 0);
;     STAGE8(SB8(0, 1), Bt, K, bcol + 128, 0); STAGE8(SA8(0, 1), A, lda, brow + 128, 0);
;   }
;   if (wr == 1) BAR8;
;   WAIT_V8(4); BAR8;
;   STAGE8(SB8(1, 0), Bt, K, bcol, 1); STAGE8(SA8(1, 0), A, lda, brow, 1); STAGE8(SB8(1, 1), Bt, K, bcol + 128, 1);
.LBB0_238:
	s_and_b64 vcc, exec, s[0:1]
	s_cbranch_vccz .LBB0_187
	s_mov_b32 s0, 25
	s_ashr_i32 s1, s0, 31
	s_lshl_b64 s[0:1], s[0:1], 3
	s_add_u32 s0, s70, s0
	s_addc_u32 s1, s71, s1
	v_readlane_b32 s2, v255, 60
	v_readlane_b32 s3, v255, 61
	s_nop 4
	s_mov_b32 s0, 25
	s_ashr_i32 s1, s0, 31
	s_lshl_b64 s[0:1], s[0:1], 3
	s_add_u32 s0, s70, s0
	s_addc_u32 s1, s71, s1
	v_readlane_b32 s4, v255, 60
	v_readlane_b32 s5, v255, 61
	s_nop 4
	s_mov_b32 s0, 25
	s_ashr_i32 s1, s0, 31
	s_lshl_b64 s[0:1], s[0:1], 3
	s_add_u32 s0, s70, s0
	s_addc_u32 s1, s71, s1
	v_mov_b32_e32 v3, v224
	v_readlane_b32 s14, v255, 60
	v_readlane_b32 s15, v255, 61
	s_nop 4
	s_ashr_i32 s53, s52, 31
	v_bfe_i32 v1, v3, 27, 1
	s_waitcnt vmcnt(10)
	v_lshlrev_b32_e32 v150, 4, v3
	s_nop 0
	v_readfirstlane_b32 s100, v150
	v_lshrrev_b32_e32 v1, 22, v1
	v_add_u32_e32 v1, v150, v1
	v_and_b32_e32 v1, 0xfffffc00, v1
	v_ashrrev_i32_e32 v0, 31, v3
	v_sub_u32_e32 v1, v150, v1
	v_lshrrev_b32_e32 v0, 26, v0
	v_lshrrev_b32_e32 v5, 4, v1
	v_add_u32_e32 v0, v3, v0
	v_bitop3_b32 v5, v5, v1, 32 bitop3:0x6c
	v_ashrrev_i32_e32 v1, 31, v1
	v_ashrrev_i32_e32 v0, 6, v0
	v_lshrrev_b32_e32 v1, 26, v1
	v_lshlrev_b32_e32 v6, 3, v0
	v_add_u32_e32 v1, v5, v1
	v_and_b32_e32 v6, -16, v6
	v_ashrrev_i32_e32 v1, 6, v1
	v_add_u32_e32 v6, v1, v6
	v_mul_i32_i24_e32 v1, 64, v1
	v_lshlrev_b32_e32 v0, 5, v0
	v_sub_u32_e32 v1, v5, v1
	v_mov_b32_e32 v14, 1
	s_waitcnt vmcnt(9)
	s_lshl_b64 s[0:1], s[52:53], 11
	v_readlane_b32 s27, v254, 44
	v_and_b32_e32 v0, 32, v0
	v_ashrrev_i16_sdwa v1, v14, sext(v1) dst_sel:DWORD dst_unused:UNUSED_PAD src0_sel:DWORD src1_sel:BYTE_0
	s_add_u32 s0, s27, s0
	v_readlane_b32 s29, v254, 45
	v_add_u32_sdwa v0, v0, sext(v1) dst_sel:DWORD dst_unused:UNUSED_PAD src0_sel:DWORD src1_sel:WORD_0
	v_ashrrev_i32_e32 v7, 31, v6
	s_addc_u32 s1, s29, s1
	v_lshlrev_b64 v[132:133], 11, v[6:7]
	v_ashrrev_i32_e32 v1, 31, v0
	v_lshl_add_u64 v[8:9], s[0:1], 0, v[132:133]
	v_lshlrev_b64 v[6:7], 1, v[0:1]
	v_lshl_add_u64 v[10:11], v[8:9], 0, v[6:7]
	v_lshrrev_b32_e32 v134, 1, v6
	v_add_u32_e32 v136, 0x20000, v132
	v_mov_b32_e32 v137, v133
	s_waitcnt vmcnt(8)
	s_or_b32 m0, s100, 0x10000
	v_lshl_add_u64 v[12:13], s[0:1], 0, v[136:137]
	global_load_lds_dwordx4 v[10:11], off
	s_or_b32 m0, s100, 0x12000
	s_lshl_b32 s0, s20, 19
	v_mov_b32_e32 v135, v7
	s_waitcnt lgkmcnt(0)
	s_add_u32 s12, s14, s0
	v_mov_b64_e32 v[8:9], v[6:7]
	s_addc_u32 s13, s15, 0
	v_lshl_add_u64 v[12:13], v[12:13], 0, v[8:9]
	v_lshl_add_u64 v[14:15], s[12:13], 0, v[132:133]
	global_load_lds_dwordx4 v[12:13], off
	s_mov_b32 m0, s100
	v_lshl_add_u64 v[14:15], v[14:15], 0, v[6:7]
	global_load_lds_dwordx4 v[14:15], off
	s_or_b32 m0, s100, 0x2000
	s_or_b32 s0, s52, 0x80
	s_ashr_i32 s1, s0, 31
	s_lshl_b64 s[20:21], s[0:1], 11
	s_add_u32 s20, s27, s20
	v_lshl_add_u64 v[16:17], s[12:13], 0, v[136:137]
	s_addc_u32 s21, s29, s21
	v_lshl_add_u64 v[16:17], v[16:17], 0, v[8:9]
	v_lshl_add_u64 v[18:19], s[20:21], 0, v[132:133]
	v_lshl_add_u64 v[20:21], s[20:21], 0, v[136:137]
	s_add_u32 s20, s12, 0x40000
	global_load_lds_dwordx4 v[16:17], off
	v_lshl_add_u64 v[18:19], v[18:19], 0, v[6:7]
	s_addc_u32 s21, s13, 0
	s_or_b32 m0, s100, 0x14000
	global_load_lds_dwordx4 v[18:19], off
	v_lshl_add_u64 v[20:21], v[20:21], 0, v[8:9]
	s_or_b32 m0, s100, 0x16000
	v_lshl_add_u64 v[22:23], s[20:21], 0, v[132:133]
	global_load_lds_dwordx4 v[20:21], off
	v_lshl_add_u64 v[22:23], v[22:23], 0, v[6:7]
	s_or_b32 m0, s100, 0x4000
	global_load_lds_dwordx4 v[22:23], off
	v_lshl_add_u64 v[22:23], s[20:21], 0, v[136:137]
	v_lshl_add_u64 v[22:23], v[22:23], 0, v[8:9]
	s_or_b32 m0, s100, 0x6000
	v_ashrrev_i32_e32 v5, 8, v3
	global_load_lds_dwordx4 v[22:23], off
	v_cmp_eq_u32_e32 vcc, 1, v5
	s_and_saveexec_b64 s[20:21], vcc
	s_cbranch_execz .LBB0_241
	s_barrier

; #define WAIT_V8(n) asm volatile("s_waitcnt vmcnt(" #n ")" ::: "memory")
; #define BAR8 __builtin_amdgcn_s_barrier()
;     ...
;   const int brow = m0, bcol = n0;
;   const int wid = t >> 6, lane = t & 63, wr = wid >> 2, wc = wid & 3, fr = lane & 15, fq = lane >> 4;
;   f32x4 acc[2][2][4][2];
;   {
;     float zinit = 0.f;
;     asm volatile("" : "+v"(zinit));
; #pragma unroll
;     for (int a = 0; a < 2; ++a)
; #pragma unroll
;       for (int b = 0; b < 2; ++b)
; #pragma unroll
;         for (int m = 0; m < 4; ++m)
; #pragma unroll
;           for (int n = 0; n < 2; ++n)
; #pragma unroll
;             for (int j = 0; j < 4; ++j) acc[a][b][m][n][j] = zinit;
;   }
;   bf16x8 At[4][2], B0[2][2], B1[2][2];
;   const int nt = K / 64;
;   if (!pre) {
;     STAGE8(SB8(0, 0), Bt, K, bcol, 0); STAGE8(SA8(0, 0), A, lda, brow, 0);
;     STAGE8(SB8(0, 1), Bt, K, bcol + 128, 0); STAGE8(SA8(0, 1), A, lda, brow + 128, 0);
;   }
;   if (wr == 1) BAR8;
;   WAIT_V8(4); BAR8;
;   STAGE8(SB8(1, 0), Bt, K, bcol, 1); STAGE8(SA8(1, 0), A, lda, brow, 1); STAGE8(SB8(1, 1), Bt, K, bcol + 128, 1);
.LBB0_551:
	s_and_b64 vcc, exec, s[0:1]
	s_cbranch_vccz .LBB0_546
	s_mov_b32 s0, 25
	s_ashr_i32 s1, s0, 31
	s_lshl_b64 s[0:1], s[0:1], 3
	s_add_u32 s0, s70, s0
	s_addc_u32 s1, s71, s1
	v_readlane_b32 s2, v255, 60
	v_readlane_b32 s3, v255, 61
	s_nop 4
	s_mov_b32 s0, 25
	s_ashr_i32 s1, s0, 31
	s_lshl_b64 s[0:1], s[0:1], 3
	s_add_u32 s0, s70, s0
	s_addc_u32 s1, s71, s1
	s_mov_b32 s12, 25
	v_readlane_b32 s0, v255, 60
	v_readlane_b32 s1, v255, 61
	s_nop 4
	s_ashr_i32 s13, s12, 31
	s_lshl_b64 s[12:13], s[12:13], 3
	s_add_u32 s12, s70, s12
	s_addc_u32 s13, s71, s13
	v_mov_b32_e32 v3, v224
	v_readlane_b32 s12, v255, 60
	v_readlane_b32 s13, v255, 61
	s_nop 4
	s_and_b32 s30, s21, 0xffffff00
	v_bfe_i32 v1, v3, 27, 1
	v_lshlrev_b32_e32 v26, 4, v3
	v_lshrrev_b32_e32 v1, 22, v1
	v_add_u32_e32 v1, v26, v1
	v_and_b32_e32 v1, 0xfffffc00, v1
	v_ashrrev_i32_e32 v0, 31, v3
	v_sub_u32_e32 v1, v26, v1
	v_lshrrev_b32_e32 v0, 26, v0
	v_lshrrev_b32_e32 v5, 4, v1
	v_add_u32_e32 v0, v3, v0
	v_bitop3_b32 v5, v5, v1, 32 bitop3:0x6c
	v_ashrrev_i32_e32 v1, 31, v1
	v_ashrrev_i32_e32 v0, 6, v0
	v_lshrrev_b32_e32 v1, 26, v1
	v_lshlrev_b32_e32 v6, 3, v0
	v_add_u32_e32 v1, v5, v1
	v_and_b32_e32 v6, -16, v6
	v_ashrrev_i32_e32 v1, 6, v1
	v_add_u32_e32 v6, v1, v6
	v_mul_i32_i24_e32 v1, 64, v1
	s_ashr_i32 s31, s30, 31
	v_lshlrev_b32_e32 v0, 5, v0
	v_sub_u32_e32 v1, v5, v1
	v_mov_b32_e32 v13, 1
	v_add_u32_e32 v27, 0x2000, v26
	s_and_b32 s36, s25, 0x3f00
	s_lshl_b64 s[14:15], s[30:31], 9
	v_and_b32_e32 v0, 32, v0
	v_ashrrev_i16_sdwa v1, v13, sext(v1) dst_sel:DWORD dst_unused:UNUSED_PAD src0_sel:DWORD src1_sel:BYTE_0
	v_ashrrev_i32_e32 v5, 31, v27
	s_add_u32 s14, s7, s14
	v_add_u32_sdwa v0, v0, sext(v1) dst_sel:DWORD dst_unused:UNUSED_PAD src0_sel:DWORD src1_sel:WORD_0
	v_ashrrev_i32_e32 v7, 31, v6
	v_lshrrev_b32_e32 v5, 22, v5
	s_addc_u32 s15, s20, s15
	v_lshlrev_b64 v[16:17], 9, v[6:7]
	v_ashrrev_i32_e32 v1, 31, v0
	v_add_u32_e32 v5, v27, v5
	v_lshl_add_u64 v[8:9], s[14:15], 0, v[16:17]
	v_lshlrev_b64 v[0:1], 1, v[0:1]
	v_ashrrev_i32_e32 v5, 10, v5
	v_lshl_add_u64 v[14:15], v[8:9], 0, v[0:1]
	v_mul_i32_i24_e32 v8, 0x400, v5
	v_sub_u32_e32 v8, v27, v8
	v_lshrrev_b32_e32 v9, 4, v8
	v_bitop3_b32 v8, v9, v8, 32 bitop3:0x6c
	v_ashrrev_i32_e32 v10, 31, v8
	v_lshrrev_b32_e32 v10, 26, v10
	v_lshlrev_b32_e32 v9, 3, v5
	v_add_u32_e32 v10, v8, v10
	v_and_b32_e32 v9, -16, v9
	v_ashrrev_i32_e32 v11, 6, v10
	v_add_u32_e32 v12, v11, v9
	v_and_b32_e32 v9, 0xc0, v10
	v_sub_u32_e32 v8, v8, v9
	v_add_u32_e32 v30, 0x10000, v26
	v_ashrrev_i16_sdwa v8, v13, sext(v8) dst_sel:DWORD dst_unused:UNUSED_PAD src0_sel:DWORD src1_sel:BYTE_0
	v_ashrrev_i32_e32 v13, 31, v12
	v_readfirstlane_b32 s27, v30
	v_add_u32_e32 v18, 0x8000, v16
	v_mov_b32_e32 v19, v17
	v_add_u32_e32 v33, 0x12000, v26
	v_mov_b32_e32 v4, v2
	s_mov_b32 m0, s27
	v_lshlrev_b32_e32 v5, 5, v5
	v_lshl_add_u64 v[10:11], s[14:15], 0, v[18:19]
	v_readfirstlane_b32 s14, v33
	global_load_lds_dwordx4 v[14:15], off
	v_and_b32_e32 v5, 32, v5
	s_mov_b32 m0, s14
	s_lshl_b32 s14, s36, 12
	v_lshrrev_b32_e32 v8, 1, v0
	s_waitcnt lgkmcnt(0)
	s_add_u32 s27, s12, s14
	v_mov_b32_e32 v9, v1
	s_addc_u32 s29, s13, 0
	v_mov_b64_e32 v[8:9], v[0:1]
	s_add_u32 s12, s27, 0x2000000
	v_lshl_add_u64 v[24:25], v[10:11], 0, v[8:9]
	s_addc_u32 s13, s29, 0
	v_lshlrev_b64 v[10:11], 12, v[6:7]
	v_lshl_add_u64 v[6:7], s[12:13], 0, v[10:11]
	v_readfirstlane_b32 s14, v26
	s_or_b32 s38, s30, 0x80
	global_load_lds_dwordx4 v[24:25], off
	v_lshl_add_u64 v[20:21], v[6:7], 0, v[0:1]
	s_mov_b32 m0, s14
	v_readfirstlane_b32 s14, v27
	s_ashr_i32 s39, s38, 31
	global_load_lds_dwordx4 v[20:21], off
	s_mov_b32 m0, s14
	s_lshl_b64 s[14:15], s[38:39], 9
	v_lshlrev_b64 v[12:13], 12, v[12:13]
	s_add_u32 s14, s7, s14
	v_lshl_add_u64 v[6:7], s[12:13], 0, v[12:13]
	s_addc_u32 s15, s20, s15
	v_add_u32_e32 v31, 0x14000, v26
	v_lshl_add_u64 v[22:23], v[6:7], 0, v[8:9]
	v_lshl_add_u64 v[6:7], s[14:15], 0, v[16:17]
	v_readfirstlane_b32 s37, v31
	v_add_u32_e32 v32, 0x16000, v26
	global_load_lds_dwordx4 v[22:23], off
	v_lshl_add_u64 v[16:17], v[6:7], 0, v[0:1]
	s_mov_b32 m0, s37
	v_lshl_add_u64 v[6:7], s[14:15], 0, v[18:19]
	v_readfirstlane_b32 s14, v32
	global_load_lds_dwordx4 v[16:17], off
	s_mov_b32 m0, s14
	s_add_u32 s14, s27, 0x2080000
	s_addc_u32 s15, s29, 0
	v_add_u32_e32 v28, 0x4000, v26
	v_lshl_add_u64 v[18:19], v[6:7], 0, v[8:9]
	v_lshl_add_u64 v[6:7], s[14:15], 0, v[10:11]
	v_readfirstlane_b32 s27, v28
	global_load_lds_dwordx4 v[18:19], off
	v_lshl_add_u64 v[6:7], v[6:7], 0, v[0:1]
	s_mov_b32 m0, s27
	v_add_u32_e32 v29, 0x6000, v26
	global_load_lds_dwordx4 v[6:7], off
	v_lshl_add_u64 v[6:7], s[14:15], 0, v[12:13]
	v_readfirstlane_b32 s14, v29
	v_lshl_add_u64 v[6:7], v[6:7], 0, v[8:9]
	s_mov_b32 m0, s14
	v_ashrrev_i32_e32 v132, 8, v3
	global_load_lds_dwordx4 v[6:7], off
	v_cmp_eq_u32_e32 vcc, 1, v132
	s_and_saveexec_b64 s[14:15], vcc
	s_cbranch_execz .LBB0_554
	s_barrier

; #define WAIT_V8(n) asm volatile("s_waitcnt vmcnt(" #n ")" ::: "memory")
; #define BAR8 __builtin_amdgcn_s_barrier()
;     ...
;   const int brow = m0, bcol = n0;
;   const int wid = t >> 6, lane = t & 63, wr = wid >> 2, wc = wid & 3, fr = lane & 15, fq = lane >> 4;
;   f32x4 acc[2][2][4][2];
;   {
;     float zinit = 0.f;
;     asm volatile("" : "+v"(zinit));
; #pragma unroll
;     for (int a = 0; a < 2; ++a)
; #pragma unroll
;       for (int b = 0; b < 2; ++b)
; #pragma unroll
;         for (int m = 0; m < 4; ++m)
; #pragma unroll
;           for (int n = 0; n < 2; ++n)
; #pragma unroll
;             for (int j = 0; j < 4; ++j) acc[a][b][m][n][j] = zinit;
;   }
;   bf16x8 At[4][2], B0[2][2], B1[2][2];
;   const int nt = K / 64;
;   if (!pre) {
;     STAGE8(SB8(0, 0), Bt, K, bcol, 0); STAGE8(SA8(0, 0), A, lda, brow, 0);
;     STAGE8(SB8(0, 1), Bt, K, bcol + 128, 0); STAGE8(SA8(0, 1), A, lda, brow + 128, 0);
;   }
;   if (wr == 1) BAR8;
;   WAIT_V8(4); BAR8;
;   STAGE8(SB8(1, 0), Bt, K, bcol, 1); STAGE8(SA8(1, 0), A, lda, brow, 1); STAGE8(SB8(1, 1), Bt, K, bcol + 128, 1);
.LBB0_905:
	s_mov_b32 s0, 24
	s_mov_b32 s0, 25
	s_ashr_i32 s1, s0, 31
	s_lshl_b64 s[0:1], s[0:1], 3
	s_add_u32 s0, s70, s0
	s_addc_u32 s1, s71, s1
	v_readlane_b32 s6, v255, 60
	v_readlane_b32 s7, v255, 61
	s_nop 4
	s_mov_b32 s0, 25
	s_ashr_i32 s1, s0, 31
	s_lshl_b64 s[0:1], s[0:1], 3
	s_add_u32 s0, s70, s0
	s_addc_u32 s1, s71, s1
	s_mov_b32 s2, 25
	v_readlane_b32 s0, v255, 60
	v_readlane_b32 s1, v255, 61
	s_nop 4
	s_ashr_i32 s3, s2, 31
	s_lshl_b64 s[2:3], s[2:3], 3
	s_add_u32 s2, s70, s2
	s_addc_u32 s3, s71, s3
	v_mov_b32_e32 v3, v224
	v_readlane_b32 s2, v255, 60
	v_readlane_b32 s3, v255, 61
	s_nop 4
	v_mov_b32_e32 v18, 1
	v_bfe_i32 v1, v3, 27, 1
	s_waitcnt vmcnt(10)
	v_lshlrev_b32_e32 v150, 4, v3
	s_nop 0
	v_readfirstlane_b32 s100, v150
	v_lshrrev_b32_e32 v1, 22, v1
	v_add_u32_e32 v1, v150, v1
	v_and_b32_e32 v1, 0xfffffc00, v1
	v_ashrrev_i32_e32 v0, 31, v3
	v_sub_u32_e32 v1, v150, v1
	v_lshrrev_b32_e32 v0, 26, v0
	v_lshrrev_b32_e32 v5, 4, v1
	v_add_u32_e32 v0, v3, v0
	v_bitop3_b32 v5, v5, v1, 32 bitop3:0x6c
	v_ashrrev_i32_e32 v1, 31, v1
	s_waitcnt lgkmcnt(0)
	s_add_u32 s29, s2, 0x6000000
	v_ashrrev_i32_e32 v0, 6, v0
	v_lshrrev_b32_e32 v1, 26, v1
	s_addc_u32 s33, s3, 0
	s_lshl_b32 s8, s24, 8
	v_lshlrev_b32_e32 v6, 3, v0
	v_add_u32_e32 v1, v5, v1
	s_and_b32 s25, s8, 0x3f00
	s_lshl_b32 s8, s24, 2
	v_and_b32_e32 v6, -16, v6
	v_ashrrev_i32_e32 v1, 6, v1
	s_and_b32 s8, s8, 0xffffff00
	v_add_u32_e32 v16, v1, v6
	v_mul_i32_i24_e32 v1, 64, v1
	s_ashr_i32 s9, s8, 31
	v_lshlrev_b32_e32 v0, 5, v0
	v_sub_u32_e32 v1, v5, v1
	s_waitcnt vmcnt(9)
	v_add_u32_e32 v152, 0x2000, v150
	s_lshl_b64 s[12:13], s[8:9], 11
	v_and_b32_e32 v0, 32, v0
	v_ashrrev_i16_sdwa v1, v18, sext(v1) dst_sel:DWORD dst_unused:UNUSED_PAD src0_sel:DWORD src1_sel:BYTE_0
	v_ashrrev_i32_e32 v5, 31, v152
	s_add_u32 s12, s14, s12
	v_add_u32_sdwa v0, v0, sext(v1) dst_sel:DWORD dst_unused:UNUSED_PAD src0_sel:DWORD src1_sel:WORD_0
	v_ashrrev_i32_e32 v17, 31, v16
	v_lshrrev_b32_e32 v5, 22, v5
	s_addc_u32 s13, s15, s13
	v_lshlrev_b64 v[6:7], 11, v[16:17]
	v_ashrrev_i32_e32 v1, 31, v0
	v_add_u32_e32 v5, v152, v5
	v_lshl_add_u64 v[10:11], s[12:13], 0, v[6:7]
	v_lshlrev_b64 v[8:9], 1, v[0:1]
	v_ashrrev_i32_e32 v5, 10, v5
	v_lshl_add_u64 v[14:15], v[10:11], 0, v[8:9]
	v_mul_i32_i24_e32 v10, 0x400, v5
	v_sub_u32_e32 v10, v152, v10
	v_lshrrev_b32_e32 v11, 4, v10
	v_bitop3_b32 v10, v11, v10, 32 bitop3:0x6c
	v_ashrrev_i32_e32 v12, 31, v10
	v_lshrrev_b32_e32 v12, 26, v12
	v_lshlrev_b32_e32 v11, 3, v5
	v_add_u32_e32 v12, v10, v12
	v_and_b32_e32 v11, -16, v11
	v_ashrrev_i32_e32 v13, 6, v12
	v_add_u32_e32 v24, v13, v11
	v_ashrrev_i32_e32 v25, 31, v24
	v_lshrrev_b32_e32 v132, 1, v8
	v_add_u32_e32 v10, 0x20000, v6
	v_mov_b32_e32 v11, v7
	s_waitcnt vmcnt(8)
	s_or_b32 m0, s100, 0x10000
	v_lshl_add_u64 v[18:19], s[12:13], 0, v[10:11]
	global_load_lds_dwordx4 v[14:15], off
	v_mov_b32_e32 v133, v9
	s_or_b32 m0, s100, 0x12000
	s_lshl_b32 s27, s25, 10
	s_lshl_b32 s12, s25, 11
	v_mov_b64_e32 v[12:13], v[8:9]
	s_add_u32 s12, s29, s12
	v_lshl_add_u64 v[18:19], v[18:19], 0, v[12:13]
	s_addc_u32 s13, s33, 0
	global_load_lds_dwordx4 v[18:19], off
	v_lshl_add_u64 v[20:21], s[12:13], 0, v[6:7]
	s_mov_b32 m0, s100
	s_or_b32 s30, s8, 0x80
	v_lshl_add_u64 v[20:21], v[20:21], 0, v[8:9]
	v_lshl_add_u64 v[22:23], s[12:13], 0, v[10:11]
	s_ashr_i32 s31, s30, 31
	global_load_lds_dwordx4 v[20:21], off
	s_or_b32 m0, s100, 0x2000
	s_lshl_b64 s[12:13], s[30:31], 11
	s_add_u32 s12, s14, s12
	s_addc_u32 s13, s15, s13
	v_lshl_add_u64 v[22:23], v[22:23], 0, v[12:13]
	v_lshl_add_u64 v[26:27], s[12:13], 0, v[6:7]
	s_bitset1_b32 s27, 17
	global_load_lds_dwordx4 v[22:23], off
	v_lshl_add_u64 v[26:27], v[26:27], 0, v[8:9]
	s_or_b32 m0, s100, 0x14000
	v_lshl_add_u64 v[28:29], s[12:13], 0, v[10:11]
	s_lshl_b32 s27, s27, 1
	global_load_lds_dwordx4 v[26:27], off
	s_or_b32 m0, s100, 0x16000
	s_add_u32 s12, s29, s27
	s_addc_u32 s13, s33, 0
	v_lshl_add_u64 v[28:29], v[28:29], 0, v[12:13]
	v_lshl_add_u64 v[30:31], s[12:13], 0, v[6:7]
	global_load_lds_dwordx4 v[28:29], off
	v_lshl_add_u64 v[30:31], v[30:31], 0, v[8:9]
	s_or_b32 m0, s100, 0x4000
	global_load_lds_dwordx4 v[30:31], off
	v_lshl_add_u64 v[30:31], s[12:13], 0, v[10:11]
	v_lshl_add_u64 v[30:31], v[30:31], 0, v[12:13]
	s_or_b32 m0, s100, 0x6000
	v_ashrrev_i32_e32 v5, 8, v3
	global_load_lds_dwordx4 v[30:31], off
	v_cmp_eq_u32_e32 vcc, 1, v5
	s_and_saveexec_b64 s[12:13], vcc
	s_cbranch_execz .LBB0_907
	s_barrier

; #define WAIT_V8(n) asm volatile("s_waitcnt vmcnt(" #n ")" ::: "memory")
; #define BAR8 __builtin_amdgcn_s_barrier()
;     ...
;   const int brow = m0, bcol = n0;
;   const int wid = t >> 6, lane = t & 63, wr = wid >> 2, wc = wid & 3, fr = lane & 15, fq = lane >> 4;
;   f32x4 acc[2][2][4][2];
;   {
;     float zinit = 0.f;
;     asm volatile("" : "+v"(zinit));
; #pragma unroll
;     for (int a = 0; a < 2; ++a)
; #pragma unroll
;       for (int b = 0; b < 2; ++b)
; #pragma unroll
;         for (int m = 0; m < 4; ++m)
; #pragma unroll
;           for (int n = 0; n < 2; ++n)
; #pragma unroll
;             for (int j = 0; j < 4; ++j) acc[a][b][m][n][j] = zinit;
;   }
;   bf16x8 At[4][2], B0[2][2], B1[2][2];
;   const int nt = K / 64;
;   if (!pre) {
;     STAGE8(SB8(0, 0), Bt, K, bcol, 0); STAGE8(SA8(0, 0), A, lda, brow, 0);
;     STAGE8(SB8(0, 1), Bt, K, bcol + 128, 0); STAGE8(SA8(0, 1), A, lda, brow + 128, 0);
;   }
;   if (wr == 1) BAR8;
;   WAIT_V8(4); BAR8;
;   STAGE8(SB8(1, 0), Bt, K, bcol, 1); STAGE8(SA8(1, 0), A, lda, brow, 1); STAGE8(SB8(1, 1), Bt, K, bcol + 128, 1);
.LBB0_1001:
	s_lshr_b32 s27, s37, 8
	s_cmpk_gt_i32 s38, 0x7f
	s_mov_b64 s[0:1], -1
	s_cbranch_scc0 .LBB0_1011
	s_mov_b32 s0, 25
	s_ashr_i32 s1, s0, 31
	s_lshl_b64 s[0:1], s[0:1], 3
	s_add_u32 s0, s70, s0
	s_addc_u32 s1, s71, s1
	v_readlane_b32 s6, v255, 60
	v_readlane_b32 s7, v255, 61
	s_nop 4
	s_mov_b32 s0, 25
	s_ashr_i32 s1, s0, 31
	s_lshl_b64 s[0:1], s[0:1], 3
	s_add_u32 s0, s70, s0
	s_addc_u32 s1, s71, s1
	v_readlane_b32 s2, v255, 60
	v_readlane_b32 s3, v255, 61
	s_nop 4
	s_mov_b32 s0, 25
	s_ashr_i32 s1, s0, 31
	s_lshl_b64 s[0:1], s[0:1], 3
	s_add_u32 s0, s70, s0
	s_addc_u32 s1, s71, s1
	v_mov_b32_e32 v3, v224
	v_readlane_b32 s12, v255, 60
	v_readlane_b32 s13, v255, 61
	s_nop 4
	s_lshl_b32 s0, s38, 8
	v_bfe_i32 v1, v3, 27, 1
	s_waitcnt vmcnt(10)
	v_lshlrev_b32_e32 v150, 4, v3
	s_nop 0
	v_readfirstlane_b32 s100, v150
	v_lshrrev_b32_e32 v1, 22, v1
	v_add_u32_e32 v1, v150, v1
	v_and_b32_e32 v1, 0xfffffc00, v1
	v_ashrrev_i32_e32 v0, 31, v3
	v_sub_u32_e32 v1, v150, v1
	v_lshrrev_b32_e32 v0, 26, v0
	v_lshrrev_b32_e32 v5, 4, v1
	v_add_u32_e32 v0, v3, v0
	v_bitop3_b32 v5, v5, v1, 32 bitop3:0x6c
	v_ashrrev_i32_e32 v1, 31, v1
	v_ashrrev_i32_e32 v0, 6, v0
	v_lshrrev_b32_e32 v1, 26, v1
	v_lshlrev_b32_e32 v6, 3, v0
	v_add_u32_e32 v1, v5, v1
	s_and_b32 s29, s0, 0x700
	s_lshl_b32 s0, s38, 5
	v_and_b32_e32 v6, -16, v6
	v_ashrrev_i32_e32 v1, 6, v1
	s_and_b32 s39, s0, 0x7fffff00
	v_add_u32_e32 v6, v1, v6
	v_mul_i32_i24_e32 v1, 64, v1
	s_add_i32 s0, s39, 0xfffff000
	v_lshlrev_b32_e32 v0, 5, v0
	v_sub_u32_e32 v1, v5, v1
	v_mov_b32_e32 v14, 1
	s_waitcnt vmcnt(9)
	s_lshl_b32 s1, s0, 11
	v_and_b32_e32 v0, 32, v0
	v_ashrrev_i16_sdwa v1, v14, sext(v1) dst_sel:DWORD dst_unused:UNUSED_PAD src0_sel:DWORD src1_sel:BYTE_0
	s_add_u32 s14, s24, s1
	v_add_u32_sdwa v0, v0, sext(v1) dst_sel:DWORD dst_unused:UNUSED_PAD src0_sel:DWORD src1_sel:WORD_0
	v_ashrrev_i32_e32 v7, 31, v6
	s_addc_u32 s15, s25, 0
	v_lshlrev_b64 v[132:133], 11, v[6:7]
	v_ashrrev_i32_e32 v1, 31, v0
	v_lshl_add_u64 v[8:9], s[14:15], 0, v[132:133]
	v_lshlrev_b64 v[6:7], 1, v[0:1]
	v_lshl_add_u64 v[10:11], v[8:9], 0, v[6:7]
	s_waitcnt vmcnt(8)
	s_or_b32 m0, s100, 0x10000
	global_load_lds_dwordx4 v[10:11], off
	s_or_b32 m0, s100, 0x12000
	s_lshl_b32 s1, s29, 11
	s_waitcnt lgkmcnt(0)
	s_add_u32 s1, s12, s1
	v_lshrrev_b32_e32 v134, 1, v6
	s_addc_u32 s40, s13, 0
	v_add_u32_e32 v136, 0x20000, v132
	v_mov_b32_e32 v137, v133
	v_mov_b32_e32 v135, v7
	s_add_u32 s8, s1, 0xb800000
	v_lshl_add_u64 v[12:13], s[14:15], 0, v[136:137]
	v_mov_b64_e32 v[8:9], v[6:7]
	s_addc_u32 s9, s40, 0
	v_lshl_add_u64 v[12:13], v[12:13], 0, v[8:9]
	v_lshl_add_u64 v[14:15], s[8:9], 0, v[132:133]
	global_load_lds_dwordx4 v[12:13], off
	s_mov_b32 m0, s100
	v_lshl_add_u64 v[16:17], v[14:15], 0, v[6:7]
	global_load_lds_dwordx4 v[16:17], off
	s_or_b32 m0, s100, 0x2000
	s_add_u32 s20, s14, 0x40000
	v_lshl_add_u64 v[14:15], s[8:9], 0, v[136:137]
	s_addc_u32 s21, s15, 0
	v_lshl_add_u64 v[14:15], v[14:15], 0, v[8:9]
	v_lshl_add_u64 v[18:19], s[20:21], 0, v[132:133]
	global_load_lds_dwordx4 v[14:15], off
	v_lshl_add_u64 v[18:19], v[18:19], 0, v[6:7]
	s_or_b32 m0, s100, 0x14000
	global_load_lds_dwordx4 v[18:19], off
	v_lshl_add_u64 v[18:19], s[20:21], 0, v[136:137]
	s_or_b32 m0, s100, 0x16000
	s_add_u32 s20, s1, 0xb840000
	v_lshl_add_u64 v[18:19], v[18:19], 0, v[8:9]
	s_addc_u32 s21, s40, 0
	global_load_lds_dwordx4 v[18:19], off
	v_lshl_add_u64 v[18:19], s[20:21], 0, v[132:133]
	v_lshl_add_u64 v[18:19], v[18:19], 0, v[6:7]
	s_or_b32 m0, s100, 0x4000
	global_load_lds_dwordx4 v[18:19], off
	v_lshl_add_u64 v[18:19], s[20:21], 0, v[136:137]
	v_lshl_add_u64 v[18:19], v[18:19], 0, v[8:9]
	s_or_b32 m0, s100, 0x6000
	v_ashrrev_i32_e32 v5, 8, v3
	global_load_lds_dwordx4 v[18:19], off
	v_cmp_eq_u32_e32 vcc, 1, v5
	s_and_saveexec_b64 s[20:21], vcc
	s_cbranch_execz .LBB0_1004
	s_barrier

; #define WAIT_V8(n) asm volatile("s_waitcnt vmcnt(" #n ")" ::: "memory")
; #define BAR8 __builtin_amdgcn_s_barrier()
;     ...
;   const int brow = m0, bcol = n0;
;   const int wid = t >> 6, lane = t & 63, wr = wid >> 2, wc = wid & 3, fr = lane & 15, fq = lane >> 4;
;   f32x4 acc[2][2][4][2];
;   {
;     float zinit = 0.f;
;     asm volatile("" : "+v"(zinit));
; #pragma unroll
;     for (int a = 0; a < 2; ++a)
; #pragma unroll
;       for (int b = 0; b < 2; ++b)
; #pragma unroll
;         for (int m = 0; m < 4; ++m)
; #pragma unroll
;           for (int n = 0; n < 2; ++n)
; #pragma unroll
;             for (int j = 0; j < 4; ++j) acc[a][b][m][n][j] = zinit;
;   }
;   bf16x8 At[4][2], B0[2][2], B1[2][2];
;   const int nt = K / 64;
;   if (!pre) {
;     STAGE8(SB8(0, 0), Bt, K, bcol, 0); STAGE8(SA8(0, 0), A, lda, brow, 0);
;     STAGE8(SB8(0, 1), Bt, K, bcol + 128, 0); STAGE8(SA8(0, 1), A, lda, brow + 128, 0);
;   }
;   if (wr == 1) BAR8;
;   WAIT_V8(4); BAR8;
;   STAGE8(SB8(1, 0), Bt, K, bcol, 1); STAGE8(SA8(1, 0), A, lda, brow, 1); STAGE8(SB8(1, 1), Bt, K, bcol + 128, 1);
.LBB0_1011:
	s_and_b64 vcc, exec, s[0:1]
	s_cbranch_vccz .LBB0_1000
	s_mov_b32 s0, 25
	s_ashr_i32 s1, s0, 31
	s_lshl_b64 s[0:1], s[0:1], 3
	s_add_u32 s0, s70, s0
	s_addc_u32 s1, s71, s1
	v_readlane_b32 s6, v255, 60
	v_readlane_b32 s7, v255, 61
	s_nop 4
	s_mov_b32 s0, 25
	s_ashr_i32 s1, s0, 31
	s_lshl_b64 s[0:1], s[0:1], 3
	s_add_u32 s0, s70, s0
	s_addc_u32 s1, s71, s1
	v_readlane_b32 s2, v255, 60
	v_readlane_b32 s3, v255, 61
	s_nop 4
	s_mov_b32 s0, 25
	s_ashr_i32 s1, s0, 31
	s_lshl_b64 s[0:1], s[0:1], 3
	s_add_u32 s0, s70, s0
	s_addc_u32 s1, s71, s1
	v_mov_b32_e32 v3, v224
	v_readlane_b32 s12, v255, 60
	v_readlane_b32 s13, v255, 61
	s_nop 4
	s_lshl_b32 s0, s38, 8
	v_bfe_i32 v1, v3, 27, 1
	s_waitcnt vmcnt(10)
	v_lshlrev_b32_e32 v150, 4, v3
	s_nop 0
	v_readfirstlane_b32 s100, v150
	v_lshrrev_b32_e32 v1, 22, v1
	v_add_u32_e32 v1, v150, v1
	v_and_b32_e32 v1, 0xfffffc00, v1
	v_ashrrev_i32_e32 v0, 31, v3
	v_sub_u32_e32 v1, v150, v1
	v_lshrrev_b32_e32 v0, 26, v0
	v_lshrrev_b32_e32 v5, 4, v1
	v_add_u32_e32 v0, v3, v0
	v_bitop3_b32 v5, v5, v1, 32 bitop3:0x6c
	v_ashrrev_i32_e32 v1, 31, v1
	v_ashrrev_i32_e32 v0, 6, v0
	v_lshrrev_b32_e32 v1, 26, v1
	v_lshlrev_b32_e32 v6, 3, v0
	v_add_u32_e32 v1, v5, v1
	s_and_b32 s20, s0, 0x3f00
	s_lshl_b32 s0, s38, 2
	v_and_b32_e32 v6, -16, v6
	v_ashrrev_i32_e32 v1, 6, v1
	s_and_b32 s0, s0, 0xffffff00
	v_add_u32_e32 v6, v1, v6
	v_mul_i32_i24_e32 v1, 64, v1
	s_ashr_i32 s1, s0, 31
	v_lshlrev_b32_e32 v0, 5, v0
	v_sub_u32_e32 v1, v5, v1
	v_mov_b32_e32 v14, 1
	s_waitcnt vmcnt(9)
	s_lshl_b64 s[8:9], s[0:1], 11
	v_and_b32_e32 v0, 32, v0
	v_ashrrev_i16_sdwa v1, v14, sext(v1) dst_sel:DWORD dst_unused:UNUSED_PAD src0_sel:DWORD src1_sel:BYTE_0
	s_add_u32 s8, s30, s8
	v_add_u32_sdwa v0, v0, sext(v1) dst_sel:DWORD dst_unused:UNUSED_PAD src0_sel:DWORD src1_sel:WORD_0
	v_ashrrev_i32_e32 v7, 31, v6
	s_addc_u32 s9, s31, s9
	v_lshlrev_b64 v[132:133], 11, v[6:7]
	v_ashrrev_i32_e32 v1, 31, v0
	v_lshl_add_u64 v[8:9], s[8:9], 0, v[132:133]
	v_lshlrev_b64 v[6:7], 1, v[0:1]
	v_lshl_add_u64 v[10:11], v[8:9], 0, v[6:7]
	v_lshrrev_b32_e32 v134, 1, v6
	v_add_u32_e32 v136, 0x20000, v132
	v_mov_b32_e32 v137, v133
	s_waitcnt vmcnt(8)
	s_or_b32 m0, s100, 0x10000
	v_lshl_add_u64 v[12:13], s[8:9], 0, v[136:137]
	global_load_lds_dwordx4 v[10:11], off
	s_or_b32 m0, s100, 0x12000
	s_lshl_b32 s8, s20, 11
	v_mov_b32_e32 v135, v7
	s_waitcnt lgkmcnt(0)
	s_add_u32 s8, s12, s8
	v_mov_b64_e32 v[8:9], v[6:7]
	s_addc_u32 s9, s13, 0
	v_lshl_add_u64 v[12:13], v[12:13], 0, v[8:9]
	v_lshl_add_u64 v[14:15], s[8:9], 0, v[132:133]
	global_load_lds_dwordx4 v[12:13], off
	s_mov_b32 m0, s100
	v_lshl_add_u64 v[14:15], v[14:15], 0, v[6:7]
	global_load_lds_dwordx4 v[14:15], off
	s_or_b32 m0, s100, 0x2000
	s_or_b32 s14, s0, 0x80
	s_ashr_i32 s15, s14, 31
	s_lshl_b64 s[14:15], s[14:15], 11
	s_add_u32 s14, s30, s14
	v_lshl_add_u64 v[16:17], s[8:9], 0, v[136:137]
	s_addc_u32 s15, s31, s15
	v_lshl_add_u64 v[16:17], v[16:17], 0, v[8:9]
	v_lshl_add_u64 v[18:19], s[14:15], 0, v[132:133]
	global_load_lds_dwordx4 v[16:17], off
	v_lshl_add_u64 v[18:19], v[18:19], 0, v[6:7]
	s_or_b32 m0, s100, 0x14000
	v_lshl_add_u64 v[20:21], s[14:15], 0, v[136:137]
	global_load_lds_dwordx4 v[18:19], off
	s_or_b32 m0, s100, 0x16000
	s_add_u32 s14, s8, 0x40000
	s_addc_u32 s15, s9, 0
	v_lshl_add_u64 v[20:21], v[20:21], 0, v[8:9]
	v_lshl_add_u64 v[22:23], s[14:15], 0, v[132:133]
	global_load_lds_dwordx4 v[20:21], off
	v_lshl_add_u64 v[22:23], v[22:23], 0, v[6:7]
	s_or_b32 m0, s100, 0x4000
	global_load_lds_dwordx4 v[22:23], off
	v_lshl_add_u64 v[22:23], s[14:15], 0, v[136:137]
	v_lshl_add_u64 v[22:23], v[22:23], 0, v[8:9]
	s_or_b32 m0, s100, 0x6000
	v_ashrrev_i32_e32 v5, 8, v3
	global_load_lds_dwordx4 v[22:23], off
	v_cmp_eq_u32_e32 vcc, 1, v5
	s_and_saveexec_b64 s[14:15], vcc
	s_cbranch_execz .LBB0_1014
	s_barrier

; #define WAIT_V8(n) asm volatile("s_waitcnt vmcnt(" #n ")" ::: "memory")
; #define BAR8 __builtin_amdgcn_s_barrier()
;     ...
;   const int brow = m0, bcol = n0;
;   const int wid = t >> 6, lane = t & 63, wr = wid >> 2, wc = wid & 3, fr = lane & 15, fq = lane >> 4;
;   f32x4 acc[2][2][4][2];
;   {
;     float zinit = 0.f;
;     asm volatile("" : "+v"(zinit));
; #pragma unroll
;     for (int a = 0; a < 2; ++a)
; #pragma unroll
;       for (int b = 0; b < 2; ++b)
; #pragma unroll
;         for (int m = 0; m < 4; ++m)
; #pragma unroll
;           for (int n = 0; n < 2; ++n)
; #pragma unroll
;             for (int j = 0; j < 4; ++j) acc[a][b][m][n][j] = zinit;
;   }
;   bf16x8 At[4][2], B0[2][2], B1[2][2];
;   const int nt = K / 64;
;   if (!pre) {
;     STAGE8(SB8(0, 0), Bt, K, bcol, 0); STAGE8(SA8(0, 0), A, lda, brow, 0);
;     STAGE8(SB8(0, 1), Bt, K, bcol + 128, 0); STAGE8(SA8(0, 1), A, lda, brow + 128, 0);
;   }
;   if (wr == 1) BAR8;
;   WAIT_V8(4); BAR8;
;   STAGE8(SB8(1, 0), Bt, K, bcol, 1); STAGE8(SA8(1, 0), A, lda, brow, 1); STAGE8(SB8(1, 1), Bt, K, bcol + 128, 1);
.LBB0_1149:
	s_mov_b32 s0, 24
	s_mov_b32 s0, 25
	s_ashr_i32 s1, s0, 31
	s_lshl_b64 s[0:1], s[0:1], 3
	s_add_u32 s0, s70, s0
	s_addc_u32 s1, s71, s1
	v_readlane_b32 s6, v255, 60
	v_readlane_b32 s7, v255, 61
	s_nop 4
	s_mov_b32 s0, 25
	s_ashr_i32 s1, s0, 31
	s_lshl_b64 s[0:1], s[0:1], 3
	s_add_u32 s0, s70, s0
	s_addc_u32 s1, s71, s1
	s_mov_b32 s2, 25
	v_readlane_b32 s0, v255, 60
	v_readlane_b32 s1, v255, 61
	s_nop 4
	s_ashr_i32 s3, s2, 31
	s_lshl_b64 s[2:3], s[2:3], 3
	s_add_u32 s2, s70, s2
	s_addc_u32 s3, s71, s3
	v_mov_b32_e32 v3, v224
	v_readlane_b32 s2, v255, 60
	v_readlane_b32 s3, v255, 61
	s_nop 4
	v_mov_b32_e32 v18, 1
	v_bfe_i32 v1, v3, 27, 1
	s_waitcnt vmcnt(10)
	v_lshlrev_b32_e32 v150, 4, v3
	s_nop 0
	v_readfirstlane_b32 s100, v150
	v_lshrrev_b32_e32 v1, 22, v1
	v_add_u32_e32 v1, v150, v1
	v_and_b32_e32 v1, 0xfffffc00, v1
	v_ashrrev_i32_e32 v0, 31, v3
	v_sub_u32_e32 v1, v150, v1
	v_lshrrev_b32_e32 v0, 26, v0
	v_lshrrev_b32_e32 v5, 4, v1
	v_add_u32_e32 v0, v3, v0
	v_bitop3_b32 v5, v5, v1, 32 bitop3:0x6c
	v_ashrrev_i32_e32 v1, 31, v1
	s_waitcnt lgkmcnt(0)
	s_add_u32 s29, s2, 0x3000000
	v_ashrrev_i32_e32 v0, 6, v0
	v_lshrrev_b32_e32 v1, 26, v1
	s_addc_u32 s33, s3, 0
	s_lshl_b32 s8, s24, 8
	v_lshlrev_b32_e32 v6, 3, v0
	v_add_u32_e32 v1, v5, v1
	s_and_b32 s25, s8, 0x3f00
	s_lshl_b32 s8, s24, 2
	v_and_b32_e32 v6, -16, v6
	v_ashrrev_i32_e32 v1, 6, v1
	s_and_b32 s8, s8, 0xffffff00
	v_add_u32_e32 v16, v1, v6
	v_mul_i32_i24_e32 v1, 64, v1
	s_ashr_i32 s9, s8, 31
	v_lshlrev_b32_e32 v0, 5, v0
	v_sub_u32_e32 v1, v5, v1
	s_waitcnt vmcnt(9)
	v_add_u32_e32 v152, 0x2000, v150
	s_lshl_b64 s[12:13], s[8:9], 10
	v_and_b32_e32 v0, 32, v0
	v_ashrrev_i16_sdwa v1, v18, sext(v1) dst_sel:DWORD dst_unused:UNUSED_PAD src0_sel:DWORD src1_sel:BYTE_0
	v_ashrrev_i32_e32 v5, 31, v152
	s_add_u32 s12, s14, s12
	v_add_u32_sdwa v0, v0, sext(v1) dst_sel:DWORD dst_unused:UNUSED_PAD src0_sel:DWORD src1_sel:WORD_0
	v_ashrrev_i32_e32 v17, 31, v16
	v_lshrrev_b32_e32 v5, 22, v5
	s_addc_u32 s13, s15, s13
	v_lshlrev_b64 v[6:7], 10, v[16:17]
	v_ashrrev_i32_e32 v1, 31, v0
	v_add_u32_e32 v5, v152, v5
	v_lshl_add_u64 v[10:11], s[12:13], 0, v[6:7]
	v_lshlrev_b64 v[8:9], 1, v[0:1]
	v_ashrrev_i32_e32 v5, 10, v5
	v_lshl_add_u64 v[14:15], v[10:11], 0, v[8:9]
	v_mul_i32_i24_e32 v10, 0x400, v5
	v_sub_u32_e32 v10, v152, v10
	v_lshrrev_b32_e32 v11, 4, v10
	v_bitop3_b32 v10, v11, v10, 32 bitop3:0x6c
	v_ashrrev_i32_e32 v12, 31, v10
	v_lshrrev_b32_e32 v12, 26, v12
	v_lshlrev_b32_e32 v11, 3, v5
	v_add_u32_e32 v12, v10, v12
	v_and_b32_e32 v11, -16, v11
	v_ashrrev_i32_e32 v13, 6, v12
	v_add_u32_e32 v24, v13, v11
	v_ashrrev_i32_e32 v25, 31, v24
	v_lshrrev_b32_e32 v132, 1, v8
	v_add_u32_e32 v10, 0x10000, v6
	v_mov_b32_e32 v11, v7
	s_waitcnt vmcnt(8)
	s_or_b32 m0, s100, 0x10000
	v_lshl_add_u64 v[18:19], s[12:13], 0, v[10:11]
	global_load_lds_dwordx4 v[14:15], off
	v_mov_b32_e32 v133, v9
	s_or_b32 m0, s100, 0x12000
	s_lshl_b32 s27, s25, 9
	s_lshl_b32 s12, s25, 10
	v_mov_b64_e32 v[12:13], v[8:9]
	s_add_u32 s12, s29, s12
	v_lshl_add_u64 v[18:19], v[18:19], 0, v[12:13]
	s_addc_u32 s13, s33, 0
	global_load_lds_dwordx4 v[18:19], off
	v_lshl_add_u64 v[20:21], s[12:13], 0, v[6:7]
	s_mov_b32 m0, s100
	s_or_b32 s30, s8, 0x80
	v_lshl_add_u64 v[20:21], v[20:21], 0, v[8:9]
	v_lshl_add_u64 v[22:23], s[12:13], 0, v[10:11]
	s_ashr_i32 s31, s30, 31
	global_load_lds_dwordx4 v[20:21], off
	s_or_b32 m0, s100, 0x2000
	s_lshl_b64 s[12:13], s[30:31], 10
	s_add_u32 s12, s14, s12
	s_addc_u32 s13, s15, s13
	v_lshl_add_u64 v[22:23], v[22:23], 0, v[12:13]
	v_lshl_add_u64 v[26:27], s[12:13], 0, v[6:7]
	s_bitset1_b32 s27, 16
	global_load_lds_dwordx4 v[22:23], off
	v_lshl_add_u64 v[26:27], v[26:27], 0, v[8:9]
	s_or_b32 m0, s100, 0x14000
	v_lshl_add_u64 v[28:29], s[12:13], 0, v[10:11]
	s_lshl_b32 s27, s27, 1
	global_load_lds_dwordx4 v[26:27], off
	s_or_b32 m0, s100, 0x16000
	s_add_u32 s12, s29, s27
	s_addc_u32 s13, s33, 0
	v_lshl_add_u64 v[28:29], v[28:29], 0, v[12:13]
	v_lshl_add_u64 v[30:31], s[12:13], 0, v[6:7]
	global_load_lds_dwordx4 v[28:29], off
	v_lshl_add_u64 v[30:31], v[30:31], 0, v[8:9]
	s_or_b32 m0, s100, 0x4000
	global_load_lds_dwordx4 v[30:31], off
	v_lshl_add_u64 v[30:31], s[12:13], 0, v[10:11]
	v_lshl_add_u64 v[30:31], v[30:31], 0, v[12:13]
	s_or_b32 m0, s100, 0x6000
	v_ashrrev_i32_e32 v5, 8, v3
	global_load_lds_dwordx4 v[30:31], off
	v_cmp_eq_u32_e32 vcc, 1, v5
	s_and_saveexec_b64 s[12:13], vcc
	s_cbranch_execz .LBB0_1151
	s_barrier

;     ...
;   if (!pre) {
;     STAGE8(SB8(0, 0), Bt, K, bcol, 0); STAGE8(SA8(0, 0), A, lda, brow, 0);
;     STAGE8(SB8(0, 1), Bt, K, bcol + 128, 0); STAGE8(SA8(0, 1), A, lda, brow + 128, 0);
;   }
.LBB0_1253:
	s_and_b64 vcc, exec, s[0:1]
	s_cbranch_vccz .LBB0_1266
	s_mov_b32 s0, 25
	s_ashr_i32 s1, s0, 31
	s_xor_b64 s[8:9], s[8:9], -1
	s_lshl_b64 s[0:1], s[0:1], 3
	s_add_u32 s0, s70, s0
	s_addc_u32 s1, s71, s1
	v_readlane_b32 s2, v255, 60
	v_readlane_b32 s3, v255, 61
	s_nop 4
	s_lshl_b32 s0, s25, 8
	v_mov_b32_e32 v3, v224
	s_and_b32 s27, s0, 0x3f00
	s_lshl_b32 s0, s25, 2
	s_and_b32 s0, s0, 0xffffff00
	s_waitcnt vmcnt(10)
	v_lshlrev_b32_e32 v150, 4, v3
	s_nop 0
	v_readfirstlane_b32 s100, v150
	v_ashrrev_i32_e32 v0, 31, v3
	v_bfe_i32 v5, v3, 27, 1
	s_andn2_b64 vcc, exec, s[8:9]
	v_lshrrev_b32_e32 v1, 26, v0
	v_lshrrev_b32_e32 v0, 22, v5
	s_waitcnt vmcnt(9)
	v_add_u32_e32 v152, 0x2000, v150
	s_waitcnt vmcnt(8)
	s_cbranch_vccnz .LBB0_1256
	v_add_u32_e32 v6, v150, v0
	v_and_b32_e32 v6, 0xfffffc00, v6
	v_sub_u32_e32 v6, v150, v6
	v_lshrrev_b32_e32 v7, 4, v6
	v_add_u32_e32 v5, v3, v1
	v_bitop3_b32 v7, v7, v6, 32 bitop3:0x6c
	v_ashrrev_i32_e32 v6, 31, v6
	v_ashrrev_i32_e32 v5, 6, v5
	v_lshrrev_b32_e32 v6, 26, v6
	v_lshlrev_b32_e32 v8, 3, v5
	v_add_u32_e32 v6, v7, v6
	v_and_b32_e32 v8, -16, v8
	v_ashrrev_i32_e32 v9, 6, v6
	v_add_u32_e32 v6, v9, v8
	v_mul_i32_i24_e32 v8, 64, v9
	s_ashr_i32 s1, s0, 31
	v_lshlrev_b32_e32 v5, 5, v5
	v_sub_u32_e32 v7, v7, v8
	v_mov_b32_e32 v14, 1
	s_lshl_b64 s[8:9], s[0:1], 11
	v_and_b32_e32 v5, 32, v5
	v_ashrrev_i16_sdwa v7, v14, sext(v7) dst_sel:DWORD dst_unused:UNUSED_PAD src0_sel:DWORD src1_sel:BYTE_0
	s_add_u32 s8, s4, s8
	v_add_u32_sdwa v8, v5, sext(v7) dst_sel:DWORD dst_unused:UNUSED_PAD src0_sel:DWORD src1_sel:WORD_0
	v_ashrrev_i32_e32 v7, 31, v6
	s_addc_u32 s9, s5, s9
	v_lshlrev_b64 v[6:7], 11, v[6:7]
	v_ashrrev_i32_e32 v9, 31, v8
	v_lshl_add_u64 v[10:11], s[8:9], 0, v[6:7]
	v_lshlrev_b64 v[8:9], 1, v[8:9]
	v_lshl_add_u64 v[10:11], v[10:11], 0, v[8:9]
	s_or_b32 m0, s100, 0x10000
	global_load_lds_dwordx4 v[10:11], off
	v_add_u32_e32 v10, 0x20000, v6
	v_mov_b32_e32 v11, v7
	s_or_b32 m0, s100, 0x12000
	s_lshl_b32 s1, s27, 11
	v_lshl_add_u64 v[14:15], s[8:9], 0, v[10:11]
	v_mov_b64_e32 v[12:13], v[8:9]
	s_waitcnt lgkmcnt(0)
	s_add_u32 s8, s2, s1
	v_lshl_add_u64 v[14:15], v[14:15], 0, v[12:13]
	s_addc_u32 s9, s3, 0
	s_or_b32 s14, s0, 0x80
	global_load_lds_dwordx4 v[14:15], off
	v_lshl_add_u64 v[14:15], s[8:9], 0, v[6:7]
	s_ashr_i32 s15, s14, 31
	v_lshl_add_u64 v[14:15], v[14:15], 0, v[8:9]
	s_mov_b32 m0, s100
	s_lshl_b64 s[14:15], s[14:15], 11
	global_load_lds_dwordx4 v[14:15], off
	v_lshl_add_u64 v[14:15], s[8:9], 0, v[10:11]
	s_add_u32 s14, s4, s14
	v_lshl_add_u64 v[14:15], v[14:15], 0, v[12:13]
	s_addc_u32 s15, s5, s15
	s_or_b32 m0, s100, 0x2000
	global_load_lds_dwordx4 v[14:15], off
	v_lshl_add_u64 v[14:15], s[14:15], 0, v[6:7]
	v_lshl_add_u64 v[14:15], v[14:15], 0, v[8:9]
	s_or_b32 m0, s100, 0x14000
	s_add_u32 s8, s8, 0x40000
	global_load_lds_dwordx4 v[14:15], off
	v_lshl_add_u64 v[14:15], s[14:15], 0, v[10:11]
	s_addc_u32 s9, s9, 0
	v_lshl_add_u64 v[14:15], v[14:15], 0, v[12:13]
	s_or_b32 m0, s100, 0x16000
	v_lshl_add_u64 v[6:7], s[8:9], 0, v[6:7]
	global_load_lds_dwordx4 v[14:15], off
	s_or_b32 m0, s100, 0x4000
	v_lshl_add_u64 v[6:7], v[6:7], 0, v[8:9]
	global_load_lds_dwordx4 v[6:7], off
	v_lshl_add_u64 v[6:7], s[8:9], 0, v[10:11]
	s_or_b32 m0, s100, 0x6000
	v_lshl_add_u64 v[6:7], v[6:7], 0, v[12:13]
	global_load_lds_dwordx4 v[6:7], off

; DI int tid_opaque() { int t = threadIdx.x; asm volatile("" : "+v"(t)); return t; }
;     ...
;   if (EPI == EPI_GU && nm0 >= 0) {
;     const int t = tid_opaque();
;     STAGE8(SB8(0, 0), Bt, K, nn0, 0); STAGE8(SA8(0, 0), A, lda, nm0, 0);
;     STAGE8(SB8(0, 1), Bt, K, nn0 + 128, 0); STAGE8(SA8(0, 1), A, lda, nm0 + 128, 0);
;   }
;     ...
;   if (t < 256) {
;     float rs = 1.f;
;     if (e.ss) {
;       const float* sp = e.ss + (size_t)(m0 + t) * e.nss;
;       float s = 0.f;
;       for (int i = 0; i < e.nss; ++i) s += sp[i];
;       rs = rsqrtf(s * e.inv_n + EPS);
.LBB0_1262:
	s_or_b64 exec, exec, s[8:9]
	v_readlane_b32 s8, v252, 1
	s_add_i32 s25, s25, s8
	v_readlane_b32 s9, v252, 2
	s_cmpk_lt_i32 s25, 0x500
	s_cselect_b64 s[8:9], -1, 0
	s_cmpk_gt_i32 s25, 0x4ff
	s_waitcnt vmcnt(0)
	s_barrier
	v_add_u32_e32 v222, s27, v3
	v_ashrrev_i32_e32 v223, 31, v222
	v_lshlrev_b64 v[222:223], 6, v[222:223]
	v_lshl_add_u64 v[222:223], s[38:39], 0, v[222:223]
	global_load_dwordx4 v[236:239], v[222:223], off
	global_load_dwordx4 v[240:243], v[222:223], off offset:16
	global_load_dwordx4 v[244:247], v[222:223], off offset:32
	global_load_dwordx4 v[248:251], v[222:223], off offset:48
	s_cbranch_scc1 .Lp7_nochain
	v_mov_b32_e32 v0, v224
	s_lshl_b32 s12, s25, 2
	v_ashrrev_i32_e32 v1, 31, v0
	v_lshrrev_b32_e32 v1, 26, v1
	v_lshlrev_b32_e32 v140, 4, v0
	v_add_u32_e32 v1, v0, v1
	v_bfe_i32 v0, v0, 27, 1
	v_lshrrev_b32_e32 v0, 22, v0
	v_add_u32_e32 v0, v140, v0
	v_and_b32_e32 v0, 0xfffffc00, v0
	v_sub_u32_e32 v0, v140, v0
	v_lshrrev_b32_e32 v132, 4, v0
	v_bitop3_b32 v132, v132, v0, 32 bitop3:0x6c
	v_ashrrev_i32_e32 v0, 31, v0
	v_ashrrev_i32_e32 v1, 6, v1
	v_lshrrev_b32_e32 v0, 26, v0
	v_lshlrev_b32_e32 v133, 3, v1
	v_add_u32_e32 v0, v132, v0
	v_and_b32_e32 v133, -16, v133
	v_ashrrev_i32_e32 v134, 6, v0
	s_and_b32 s12, s12, 0xffffff00
	v_add_u32_e32 v0, v134, v133
	v_mul_i32_i24_e32 v133, 64, v134
	s_lshl_b32 s1, s25, 19
	s_ashr_i32 s13, s12, 31
	v_lshlrev_b32_e32 v1, 5, v1
	v_sub_u32_e32 v132, v132, v133
	v_mov_b32_e32 v139, 1
	s_and_b32 s1, s1, 0x1f80000
	s_lshl_b64 s[14:15], s[12:13], 11
	v_and_b32_e32 v1, 32, v1
	v_ashrrev_i16_sdwa v132, v139, sext(v132) dst_sel:DWORD dst_unused:UNUSED_PAD src0_sel:DWORD src1_sel:BYTE_0
	s_add_u32 s14, s4, s14
	v_add_u32_sdwa v132, v1, sext(v132) dst_sel:DWORD dst_unused:UNUSED_PAD src0_sel:DWORD src1_sel:WORD_0
	v_ashrrev_i32_e32 v1, 31, v0
	s_addc_u32 s15, s5, s15
	v_lshlrev_b64 v[0:1], 11, v[0:1]
	v_ashrrev_i32_e32 v133, 31, v132
	v_add_u32_e32 v136, 0x10000, v140
	v_lshl_add_u64 v[134:135], s[14:15], 0, v[0:1]
	v_lshlrev_b64 v[132:133], 1, v[132:133]
	v_readfirstlane_b32 s13, v136
	v_lshl_add_u64 v[134:135], v[134:135], 0, v[132:133]
	s_mov_b32 m0, s13
	v_add_u32_e32 v141, 0x2000, v140
	global_load_lds_dwordx4 v[134:135], off
	v_add_u32_e32 v134, 0x20000, v0
	v_mov_b32_e32 v135, v1
	v_add_u32_e32 v142, 0x12000, v140
	s_add_u32 s2, s2, s1
	v_lshl_add_u64 v[138:139], s[14:15], 0, v[134:135]
	v_mov_b64_e32 v[136:137], v[132:133]
	v_readfirstlane_b32 s13, v142
	s_addc_u32 s3, s3, 0
	s_bitset1_b32 s12, 7
	v_lshl_add_u64 v[138:139], v[138:139], 0, v[136:137]
	s_mov_b32 m0, s13
	s_ashr_i32 s13, s12, 31
	global_load_lds_dwordx4 v[138:139], off
	v_lshl_add_u64 v[138:139], s[2:3], 0, v[0:1]
	v_readfirstlane_b32 s1, v140
	s_lshl_b64 s[12:13], s[12:13], 11
	v_lshl_add_u64 v[138:139], v[138:139], 0, v[132:133]
	s_mov_b32 m0, s1
	s_add_u32 s12, s4, s12
	global_load_lds_dwordx4 v[138:139], off
	v_lshl_add_u64 v[138:139], s[2:3], 0, v[134:135]
	v_readfirstlane_b32 s1, v141
	s_addc_u32 s13, s5, s13
	v_lshl_add_u64 v[138:139], v[138:139], 0, v[136:137]
	s_mov_b32 m0, s1
	v_add_u32_e32 v141, 0x14000, v140
	s_add_u32 s2, s2, 0x40000
	global_load_lds_dwordx4 v[138:139], off
	v_lshl_add_u64 v[138:139], s[12:13], 0, v[0:1]
	v_readfirstlane_b32 s1, v141
	s_addc_u32 s3, s3, 0
	v_lshl_add_u64 v[138:139], v[138:139], 0, v[132:133]
	s_mov_b32 m0, s1
	v_add_u32_e32 v141, 0x16000, v140
	v_lshl_add_u64 v[0:1], s[2:3], 0, v[0:1]
	global_load_lds_dwordx4 v[138:139], off
	v_lshl_add_u64 v[138:139], s[12:13], 0, v[134:135]
	v_readfirstlane_b32 s1, v141
	v_lshl_add_u64 v[0:1], v[0:1], 0, v[132:133]
	v_add_u32_e32 v132, 0x4000, v140
	v_lshl_add_u64 v[138:139], v[138:139], 0, v[136:137]
	s_mov_b32 m0, s1
	v_readfirstlane_b32 s1, v132
	global_load_lds_dwordx4 v[138:139], off
	s_mov_b32 m0, s1
	v_add_u32_e32 v132, 0x6000, v140
	global_load_lds_dwordx4 v[0:1], off
	v_lshl_add_u64 v[0:1], s[2:3], 0, v[134:135]
	v_readfirstlane_b32 s1, v132
	v_lshl_add_u64 v[0:1], v[0:1], 0, v[136:137]
	s_mov_b32 m0, s1
	s_nop 0
	global_load_lds_dwordx4 v[0:1], off
	s_branch .LBB0_1264

; #define WAIT_V8(n) asm volatile("s_waitcnt vmcnt(" #n ")" ::: "memory")
; #define BAR8 __builtin_amdgcn_s_barrier()
;     ...
;   const int brow = m0, bcol = n0;
;   const int wid = t >> 6, lane = t & 63, wr = wid >> 2, wc = wid & 3, fr = lane & 15, fq = lane >> 4;
;   f32x4 acc[2][2][4][2];
;   {
;     float zinit = 0.f;
;     asm volatile("" : "+v"(zinit));
; #pragma unroll
;     for (int a = 0; a < 2; ++a)
; #pragma unroll
;       for (int b = 0; b < 2; ++b)
; #pragma unroll
;         for (int m = 0; m < 4; ++m)
; #pragma unroll
;           for (int n = 0; n < 2; ++n)
; #pragma unroll
;             for (int j = 0; j < 4; ++j) acc[a][b][m][n][j] = zinit;
;   }
;   bf16x8 At[4][2], B0[2][2], B1[2][2];
;   const int nt = K / 64;
;   if (!pre) {
;     STAGE8(SB8(0, 0), Bt, K, bcol, 0); STAGE8(SA8(0, 0), A, lda, brow, 0);
;     STAGE8(SB8(0, 1), Bt, K, bcol + 128, 0); STAGE8(SA8(0, 1), A, lda, brow + 128, 0);
;   }
;   if (wr == 1) BAR8;
;   WAIT_V8(4); BAR8;
;   STAGE8(SB8(1, 0), Bt, K, bcol, 1); STAGE8(SA8(1, 0), A, lda, brow, 1); STAGE8(SB8(1, 1), Bt, K, bcol + 128, 1);
.LBB0_1322:
	s_mov_b32 s0, 24
	s_mov_b32 s0, 25
	s_ashr_i32 s1, s0, 31
	s_lshl_b64 s[0:1], s[0:1], 3
	s_add_u32 s0, s70, s0
	s_addc_u32 s1, s71, s1
	v_readlane_b32 s6, v255, 60
	v_readlane_b32 s7, v255, 61
	s_nop 4
	s_mov_b32 s0, 25
	s_ashr_i32 s1, s0, 31
	s_lshl_b64 s[0:1], s[0:1], 3
	s_add_u32 s0, s70, s0
	s_addc_u32 s1, s71, s1
	s_mov_b32 s2, 25
	v_readlane_b32 s0, v255, 60
	v_readlane_b32 s1, v255, 61
	s_nop 4
	s_ashr_i32 s3, s2, 31
	s_lshl_b64 s[2:3], s[2:3], 3
	s_add_u32 s2, s70, s2
	s_addc_u32 s3, s71, s3
	v_mov_b32_e32 v3, v224
	v_readlane_b32 s2, v255, 60
	v_readlane_b32 s3, v255, 61
	s_nop 4
	s_lshl_b32 s8, s24, 8
	v_bfe_i32 v1, v3, 27, 1
	s_waitcnt vmcnt(10)
	v_lshlrev_b32_e32 v150, 4, v3
	s_nop 0
	v_readfirstlane_b32 s100, v150
	v_lshrrev_b32_e32 v1, 22, v1
	v_add_u32_e32 v1, v150, v1
	v_and_b32_e32 v1, 0xfffffc00, v1
	v_ashrrev_i32_e32 v0, 31, v3
	v_sub_u32_e32 v1, v150, v1
	v_lshrrev_b32_e32 v0, 26, v0
	v_lshrrev_b32_e32 v5, 4, v1
	v_add_u32_e32 v0, v3, v0
	v_bitop3_b32 v6, v5, v1, 32 bitop3:0x6c
	v_ashrrev_i32_e32 v1, 31, v1
	v_ashrrev_i32_e32 v0, 6, v0
	v_lshrrev_b32_e32 v1, 26, v1
	v_lshlrev_b32_e32 v5, 3, v0
	v_add_u32_e32 v1, v6, v1
	v_and_b32_e32 v5, -16, v5
	v_ashrrev_i32_e32 v1, 6, v1
	s_and_b32 s25, s8, 0x3f00
	s_lshl_b32 s8, s24, 2
	v_add_u32_e32 v5, v1, v5
	v_mul_i32_i24_e32 v1, 64, v1
	s_and_b32 s8, s8, 0xffffff00
	v_lshlrev_b32_e32 v0, 5, v0
	v_sub_u32_e32 v1, v6, v1
	v_mov_b32_e32 v15, 1
	s_mul_i32 s12, s8, 0x1600
	v_and_b32_e32 v0, 32, v0
	v_ashrrev_i16_sdwa v1, v15, sext(v1) dst_sel:DWORD dst_unused:UNUSED_PAD src0_sel:DWORD src1_sel:BYTE_0
	s_movk_i32 s27, 0xb00
	s_mul_hi_i32 s9, s8, 0x1600
	s_add_u32 s12, s14, s12
	v_add_u32_sdwa v0, v0, sext(v1) dst_sel:DWORD dst_unused:UNUSED_PAD src0_sel:DWORD src1_sel:WORD_0
	v_mad_i64_i32 v[132:133], s[30:31], v5, s27, 0
	s_addc_u32 s13, s15, s9
	v_lshlrev_b64 v[24:25], 1, v[132:133]
	v_ashrrev_i32_e32 v1, 31, v0
	v_lshl_add_u64 v[8:9], s[12:13], 0, v[24:25]
	v_lshlrev_b64 v[6:7], 1, v[0:1]
	s_waitcnt vmcnt(9)
	v_add_u32_e32 v152, 0x2000, v150
	v_lshl_add_u64 v[10:11], v[8:9], 0, v[6:7]
	v_ashrrev_i32_e32 v8, 31, v152
	v_lshrrev_b32_e32 v8, 22, v8
	v_add_u32_e32 v8, v152, v8
	v_ashrrev_i32_e32 v8, 10, v8
	v_mul_i32_i24_e32 v9, 0x400, v8
	v_sub_u32_e32 v9, v152, v9
	v_lshrrev_b32_e32 v12, 4, v9
	v_bitop3_b32 v9, v12, v9, 32 bitop3:0x6c
	v_ashrrev_i32_e32 v13, 31, v9
	v_lshrrev_b32_e32 v13, 26, v13
	v_lshlrev_b32_e32 v12, 3, v8
	v_add_u32_e32 v13, v9, v13
	s_waitcnt vmcnt(8)
	s_or_b32 m0, s100, 0x10000
	v_and_b32_e32 v12, -16, v12
	v_ashrrev_i32_e32 v14, 6, v13
	global_load_lds_dwordx4 v[10:11], off
	v_add_u32_e32 v22, v14, v12
	v_and_b32_e32 v12, 0xc0, v13
	s_or_b32 m0, s100, 0x12000
	s_mul_i32 s9, s25, 0xb00
	v_lshlrev_b32_e32 v8, 5, v8
	v_sub_u32_e32 v9, v9, v12
	v_mad_i64_i32 v[136:137], s[30:31], v22, s27, 0
	s_lshl_b32 s27, s9, 1
	v_and_b32_e32 v8, 32, v8
	v_ashrrev_i16_sdwa v9, v15, sext(v9) dst_sel:DWORD dst_unused:UNUSED_PAD src0_sel:DWORD src1_sel:BYTE_0
	s_waitcnt lgkmcnt(0)
	s_add_u32 s9, s2, s27
	v_add_u32_sdwa v134, v8, sext(v9) dst_sel:DWORD dst_unused:UNUSED_PAD src0_sel:DWORD src1_sel:WORD_0
	v_lshlrev_b64 v[26:27], 1, v[136:137]
	s_addc_u32 s29, s3, 0
	v_lshl_add_u64 v[12:13], s[12:13], 0, v[26:27]
	v_ashrrev_i32_e32 v135, 31, v134
	s_add_u32 s12, s9, 0x2000000
	v_lshlrev_b64 v[8:9], 1, v[134:135]
	s_addc_u32 s13, s29, 0
	v_lshl_add_u64 v[12:13], v[12:13], 0, v[8:9]
	v_lshl_add_u64 v[14:15], s[12:13], 0, v[24:25]
	global_load_lds_dwordx4 v[12:13], off
	v_lshl_add_u64 v[14:15], v[14:15], 0, v[6:7]
	s_mov_b32 m0, s100
	v_lshl_add_u64 v[16:17], s[12:13], 0, v[26:27]
	s_or_b32 s30, s8, 0x80
	global_load_lds_dwordx4 v[14:15], off
	s_or_b32 m0, s100, 0x2000
	s_mul_i32 s12, s30, 0x1600
	s_mul_hi_i32 s13, s30, 0x1600
	s_add_u32 s12, s14, s12
	s_addc_u32 s13, s15, s13
	v_lshl_add_u64 v[16:17], v[16:17], 0, v[8:9]
	v_lshl_add_u64 v[18:19], s[12:13], 0, v[24:25]
	global_load_lds_dwordx4 v[16:17], off
	v_lshl_add_u64 v[18:19], v[18:19], 0, v[6:7]
	s_or_b32 m0, s100, 0x14000
	v_lshl_add_u64 v[20:21], s[12:13], 0, v[26:27]
	global_load_lds_dwordx4 v[18:19], off
	s_or_b32 m0, s100, 0x16000
	s_add_u32 s12, s9, 0x20b0000
	s_addc_u32 s13, s29, 0
	v_lshl_add_u64 v[20:21], v[20:21], 0, v[8:9]
	v_lshl_add_u64 v[24:25], s[12:13], 0, v[24:25]
	global_load_lds_dwordx4 v[20:21], off
	v_lshl_add_u64 v[24:25], v[24:25], 0, v[6:7]
	s_or_b32 m0, s100, 0x4000
	global_load_lds_dwordx4 v[24:25], off
	v_lshl_add_u64 v[24:25], s[12:13], 0, v[26:27]
	v_lshl_add_u64 v[24:25], v[24:25], 0, v[8:9]
	s_or_b32 m0, s100, 0x6000
	v_ashrrev_i32_e32 v23, 8, v3
	global_load_lds_dwordx4 v[24:25], off
	v_cmp_eq_u32_e32 vcc, 1, v23
	s_and_saveexec_b64 s[12:13], vcc
	s_cbranch_execz .LBB0_1324
	s_barrier
